# P1 epilogue: store addresses of row groups 1..7 by one 64-bit add from group 0 (on top of the LRU interior prefetch path)
# speedup vs baseline: 1.0034x; 1.0034x over previous
.LBB0_165:
	v_lshl_or_b32 v146, s33, 8, v150
	v_lshl_add_u32 v156, s84, 8, v148
	v_ashrrev_i32_e32 v147, 31, v146
	v_mov_b64_e32 v[144:145], s[38:39]
	v_mad_i64_i32 v[154:155], s[0:1], v156, s95, v[144:145]
	v_lshlrev_b64 v[146:147], 1, v[146:147]
	v_lshl_add_u64 v[154:155], v[154:155], 0, v[146:147]
	v_mov_b64_e32 v[242:243], v[154:155]
	s_mov_b32 s99, 0
	v_cvt_pk_bf16_f32 v124, v124, v125
	v_cvt_pk_bf16_f32 v125, v126, v127
	v_cvt_pk_bf16_f32 v126, v120, v121
	v_cvt_pk_bf16_f32 v127, v122, v123
	global_store_dwordx4 v[154:155], v[124:127], off
	v_cvt_pk_bf16_f32 v112, v112, v113
	v_cvt_pk_bf16_f32 v113, v114, v115
	v_cvt_pk_bf16_f32 v114, v104, v105
	v_cvt_pk_bf16_f32 v115, v106, v107
	global_store_dwordx4 v[154:155], v[112:115], off offset:256
	s_andn2_b64 vcc, exec, s[2:3]
	s_mov_b64 s[2:3], -1
	s_mov_b32 s98, 0xe000
	v_lshl_add_u64 v[112:113], v[242:243], 0, s[98:99]
	v_cvt_pk_bf16_f32 v104, v116, v117
	v_cvt_pk_bf16_f32 v105, v118, v119
	v_cvt_pk_bf16_f32 v106, v108, v109
	v_cvt_pk_bf16_f32 v107, v110, v111
	global_store_dwordx4 v[112:113], v[104:107], off
	v_cvt_pk_bf16_f32 v96, v96, v97
	v_cvt_pk_bf16_f32 v97, v98, v99
	v_cvt_pk_bf16_f32 v98, v88, v89
	v_cvt_pk_bf16_f32 v99, v90, v91
	global_store_dwordx4 v[112:113], v[96:99], off offset:256
	s_mov_b32 s70, s97
	s_nop 0
	s_mov_b32 s98, 0x1c000
	v_lshl_add_u64 v[96:97], v[242:243], 0, s[98:99]
	v_cvt_pk_bf16_f32 v88, v100, v101
	v_cvt_pk_bf16_f32 v89, v102, v103
	v_cvt_pk_bf16_f32 v90, v92, v93
	v_cvt_pk_bf16_f32 v91, v94, v95
	global_store_dwordx4 v[96:97], v[88:91], off
	v_cvt_pk_bf16_f32 v80, v80, v81
	v_cvt_pk_bf16_f32 v81, v82, v83
	v_cvt_pk_bf16_f32 v82, v72, v73
	v_cvt_pk_bf16_f32 v83, v74, v75
	global_store_dwordx4 v[96:97], v[80:83], off offset:256
	s_nop 1
	s_mov_b32 s98, 0x2a000
	v_lshl_add_u64 v[80:81], v[242:243], 0, s[98:99]
	v_cvt_pk_bf16_f32 v72, v84, v85
	v_cvt_pk_bf16_f32 v73, v86, v87
	v_cvt_pk_bf16_f32 v74, v76, v77
	v_cvt_pk_bf16_f32 v75, v78, v79
	global_store_dwordx4 v[80:81], v[72:75], off
	v_cvt_pk_bf16_f32 v68, v68, v69
	v_cvt_pk_bf16_f32 v69, v70, v71
	v_cvt_pk_bf16_f32 v70, v64, v65
	s_mov_b32 s98, 0x70000
	v_lshl_add_u64 v[64:65], v[242:243], 0, s[98:99]
	v_cvt_pk_bf16_f32 v71, v66, v67
	global_store_dwordx4 v[80:81], v[68:71], off offset:256
	v_cvt_pk_bf16_f32 v60, v60, v61
	v_cvt_pk_bf16_f32 v61, v62, v63
	v_cvt_pk_bf16_f32 v62, v56, v57
	v_cvt_pk_bf16_f32 v63, v58, v59
	global_store_dwordx4 v[64:65], v[60:63], off
	v_cvt_pk_bf16_f32 v48, v48, v49
	v_cvt_pk_bf16_f32 v49, v50, v51
	v_cvt_pk_bf16_f32 v50, v40, v41
	v_cvt_pk_bf16_f32 v51, v42, v43
	global_store_dwordx4 v[64:65], v[48:51], off offset:256
	s_nop 1
	s_mov_b32 s98, 0x7e000
	v_lshl_add_u64 v[48:49], v[242:243], 0, s[98:99]
	v_cvt_pk_bf16_f32 v40, v52, v53
	v_cvt_pk_bf16_f32 v41, v54, v55
	v_cvt_pk_bf16_f32 v42, v44, v45
	v_cvt_pk_bf16_f32 v43, v46, v47
	global_store_dwordx4 v[48:49], v[40:43], off
	v_cvt_pk_bf16_f32 v32, v32, v33
	v_cvt_pk_bf16_f32 v33, v34, v35
	v_cvt_pk_bf16_f32 v34, v24, v25
	v_cvt_pk_bf16_f32 v35, v26, v27
	global_store_dwordx4 v[48:49], v[32:35], off offset:256
	s_nop 1
	s_mov_b32 s98, 0x8c000
	v_lshl_add_u64 v[32:33], v[242:243], 0, s[98:99]
	v_cvt_pk_bf16_f32 v24, v36, v37
	v_cvt_pk_bf16_f32 v25, v38, v39
	v_cvt_pk_bf16_f32 v26, v28, v29
	v_cvt_pk_bf16_f32 v27, v30, v31
	global_store_dwordx4 v[32:33], v[24:27], off
	v_cvt_pk_bf16_f32 v16, v16, v17
	v_cvt_pk_bf16_f32 v17, v18, v19
	v_cvt_pk_bf16_f32 v18, v8, v9
	v_cvt_pk_bf16_f32 v19, v10, v11
	global_store_dwordx4 v[32:33], v[16:19], off offset:256
	s_nop 1
	s_mov_b32 s98, 0x9a000
	v_lshl_add_u64 v[16:17], v[242:243], 0, s[98:99]
	v_cvt_pk_bf16_f32 v8, v20, v21
	v_cvt_pk_bf16_f32 v9, v22, v23
	v_cvt_pk_bf16_f32 v10, v12, v13
	v_cvt_pk_bf16_f32 v11, v14, v15
	global_store_dwordx4 v[16:17], v[8:11], off
	v_cvt_pk_bf16_f32 v4, v4, v5
	v_cvt_pk_bf16_f32 v5, v6, v7
	v_cvt_pk_bf16_f32 v6, v0, v1
	v_cvt_pk_bf16_f32 v7, v2, v3
	global_store_dwordx4 v[16:17], v[4:7], off offset:256
	s_cbranch_vccnz .LBB0_158
	s_andn2_b64 vcc, exec, s[6:7]
	s_cbranch_vccnz .LBB0_157
	s_barrier
	s_branch .LBB0_157
